# post-FFN rms / final-norm phase: row outputs (XN bf16, final f32) stored write-through (sc1) so nothing dirty remains for the end-of-kernel write-back
# baseline (speedup 1.0000x reference)
; __device__ __forceinline__ u32x4 pack8(const f32x4 a, const f32x4 b) { u32x4 w; w.x = cvt_pk_bf16(a[0], a[1]); w.y = cvt_pk_bf16(a[2], a[3]); w.z = cvt_pk_bf16(b[0], b[1]); w.w = cvt_pk_bf16(b[2], b[3]); return w; }
;     __device__ __forceinline__ void operator()(const f32x4 (&acc)[2][2][4][2], const Unit& u, int wr, int wc, int fr, int fq) const {
;     ...
;             for (int m = 0; m < 4; ++m) { const size_t off = (size_t)(row0 + ai * HALF + m * 16) * 1024 + col0;
; #pragma unroll
;                 for (int bj = 0; bj < 2; ++bj) { const u32x4 gw = *(const u32x4*)(Gt + off + bj * HALF);
;                     f32x4 v0 = acc[ai][bj][m][0], v1 = acc[ai][bj][m][1];
;                     v0[0] *= bflo(gw.x); v0[1] *= bfhi(gw.x); v0[2] *= bflo(gw.y); v0[3] *= bfhi(gw.y);
;                     v1[0] *= bflo(gw.z); v1[1] *= bfhi(gw.z); v1[2] *= bflo(gw.w); v1[3] *= bfhi(gw.w);
;                     if (ADD) { const u32x4 pw = *(const u32x4*)(MG + off + bj * HALF);
;                         v0[0] += bflo(pw.x); v0[1] += bfhi(pw.x); v0[2] += bflo(pw.y); v0[3] += bfhi(pw.y);
;                         v1[0] += bflo(pw.z); v1[1] += bfhi(pw.z); v1[2] += bflo(pw.w); v1[3] += bfhi(pw.w); }
;                     *(u32x4*)(MG + off + bj * HALF) = pack8(v0, v1); }
;                 asm volatile("" ::: "memory"); }
.LBB0_728:
	s_mov_b64 s[18:19], s[16:17]
	s_mov_b64 s[38:39], s[14:15]
	s_waitcnt vmcnt(14)
	v_lshlrev_b32_e32 v145, 16, v140
	v_lshlrev_b32_e32 v149, 16, v150
	v_and_b32_e32 v140, 0xffff0000, v140
	v_and_b32_e32 v150, 0xffff0000, v150
	v_fmac_f32_e32 v149, v124, v145
	v_fmac_f32_e32 v150, v125, v140
	v_cvt_pk_bf16_f32 v140, v149, v150
	v_lshlrev_b32_e32 v145, 16, v141
	v_lshlrev_b32_e32 v149, 16, v151
	v_and_b32_e32 v141, 0xffff0000, v141
	v_and_b32_e32 v151, 0xffff0000, v151
	v_fmac_f32_e32 v149, v126, v145
	v_fmac_f32_e32 v151, v127, v141
	v_cvt_pk_bf16_f32 v141, v149, v151
	v_lshlrev_b32_e32 v145, 16, v142
	v_lshlrev_b32_e32 v149, 16, v152
	v_and_b32_e32 v142, 0xffff0000, v142
	v_and_b32_e32 v152, 0xffff0000, v152
	v_fmac_f32_e32 v149, v120, v145
	v_fmac_f32_e32 v152, v121, v142
	v_cvt_pk_bf16_f32 v142, v149, v152
	v_lshlrev_b32_e32 v145, 16, v143
	v_lshlrev_b32_e32 v149, 16, v153
	v_and_b32_e32 v143, 0xffff0000, v143
	v_and_b32_e32 v153, 0xffff0000, v153
	v_fmac_f32_e32 v149, v122, v145
	v_fmac_f32_e32 v153, v123, v143
	v_cvt_pk_bf16_f32 v143, v149, v153
	global_store_dwordx4 v144, v[140:143], s[38:39] sc1
	v_add_u32_e32 v145, 0x40000, v144
	global_load_dwordx4 v[150:153], v145, s[38:39]
	global_load_dwordx4 v[140:143], v145, s[18:19]
	s_waitcnt vmcnt(15)
	v_lshlrev_b32_e32 v145, 16, v154
	v_lshlrev_b32_e32 v149, 16, v158
	v_and_b32_e32 v154, 0xffff0000, v154
	v_and_b32_e32 v158, 0xffff0000, v158
	v_fmac_f32_e32 v149, v116, v145
	v_fmac_f32_e32 v158, v117, v154
	v_cvt_pk_bf16_f32 v154, v149, v158
	v_lshlrev_b32_e32 v145, 16, v155
	v_lshlrev_b32_e32 v149, 16, v159
	v_and_b32_e32 v155, 0xffff0000, v155
	v_and_b32_e32 v159, 0xffff0000, v159
	v_fmac_f32_e32 v149, v118, v145
	v_fmac_f32_e32 v159, v119, v155
	v_cvt_pk_bf16_f32 v155, v149, v159
	v_lshlrev_b32_e32 v145, 16, v156
	v_lshlrev_b32_e32 v149, 16, v160
	v_and_b32_e32 v156, 0xffff0000, v156
	v_and_b32_e32 v160, 0xffff0000, v160
	v_fmac_f32_e32 v149, v112, v145
	v_fmac_f32_e32 v160, v113, v156
	v_cvt_pk_bf16_f32 v156, v149, v160
	v_lshlrev_b32_e32 v145, 16, v157
	v_lshlrev_b32_e32 v149, 16, v161
	v_and_b32_e32 v157, 0xffff0000, v157
	v_and_b32_e32 v161, 0xffff0000, v161
	v_fmac_f32_e32 v149, v114, v145
	v_fmac_f32_e32 v161, v115, v157
	v_cvt_pk_bf16_f32 v157, v149, v161
	global_store_dwordx4 v144, v[154:157], s[38:39] offset:256 sc1
	v_add_u32_e32 v145, 0x40000, v144
	global_load_dwordx4 v[158:161], v145, s[38:39] offset:256
	global_load_dwordx4 v[154:157], v145, s[18:19] offset:256
	s_add_u32 s18, s16, 0x8000
	s_addc_u32 s19, s17, 0
	s_add_u32 s38, s14, 0x8000
	s_addc_u32 s39, s15, 0
	s_waitcnt vmcnt(16)
	v_lshlrev_b32_e32 v145, 16, v162
	v_lshlrev_b32_e32 v149, 16, v166
	v_and_b32_e32 v162, 0xffff0000, v162
	v_and_b32_e32 v166, 0xffff0000, v166
	v_fmac_f32_e32 v149, v108, v145
	v_fmac_f32_e32 v166, v109, v162
	v_cvt_pk_bf16_f32 v162, v149, v166
	v_lshlrev_b32_e32 v145, 16, v163
	v_lshlrev_b32_e32 v149, 16, v167
	v_and_b32_e32 v163, 0xffff0000, v163
	v_and_b32_e32 v167, 0xffff0000, v167
	v_fmac_f32_e32 v149, v110, v145
	v_fmac_f32_e32 v167, v111, v163
	v_cvt_pk_bf16_f32 v163, v149, v167
	v_lshlrev_b32_e32 v145, 16, v164
	v_lshlrev_b32_e32 v149, 16, v168
	v_and_b32_e32 v164, 0xffff0000, v164
	v_and_b32_e32 v168, 0xffff0000, v168
	v_fmac_f32_e32 v149, v104, v145
	v_fmac_f32_e32 v168, v105, v164
	v_cvt_pk_bf16_f32 v164, v149, v168
	v_lshlrev_b32_e32 v145, 16, v165
	v_lshlrev_b32_e32 v149, 16, v169
	v_and_b32_e32 v165, 0xffff0000, v165
	v_and_b32_e32 v169, 0xffff0000, v169
	v_fmac_f32_e32 v149, v106, v145
	v_fmac_f32_e32 v169, v107, v165
	v_cvt_pk_bf16_f32 v165, v149, v169
	global_store_dwordx4 v144, v[162:165], s[38:39] sc1
	v_add_u32_e32 v145, 0x40000, v144
	global_load_dwordx4 v[166:169], v145, s[38:39]
	global_load_dwordx4 v[162:165], v145, s[18:19]
	s_waitcnt vmcnt(17)
	v_lshlrev_b32_e32 v145, 16, v170
	v_lshlrev_b32_e32 v149, 16, v174
	v_and_b32_e32 v170, 0xffff0000, v170
	v_and_b32_e32 v174, 0xffff0000, v174
	v_fmac_f32_e32 v149, v100, v145
	v_fmac_f32_e32 v174, v101, v170
	v_cvt_pk_bf16_f32 v170, v149, v174
	v_lshlrev_b32_e32 v145, 16, v171
	v_lshlrev_b32_e32 v149, 16, v175
	v_and_b32_e32 v171, 0xffff0000, v171
	v_and_b32_e32 v175, 0xffff0000, v175
	v_fmac_f32_e32 v149, v102, v145
	v_fmac_f32_e32 v175, v103, v171
	v_cvt_pk_bf16_f32 v171, v149, v175
	v_lshlrev_b32_e32 v145, 16, v172
	v_lshlrev_b32_e32 v149, 16, v176
	v_and_b32_e32 v172, 0xffff0000, v172
	v_and_b32_e32 v176, 0xffff0000, v176
	v_fmac_f32_e32 v149, v96, v145
	v_fmac_f32_e32 v176, v97, v172
	v_cvt_pk_bf16_f32 v172, v149, v176
	v_lshlrev_b32_e32 v145, 16, v173
	v_lshlrev_b32_e32 v149, 16, v177
	v_and_b32_e32 v173, 0xffff0000, v173
	v_and_b32_e32 v177, 0xffff0000, v177
	v_fmac_f32_e32 v149, v98, v145
	v_fmac_f32_e32 v177, v99, v173
	v_cvt_pk_bf16_f32 v173, v149, v177
	global_store_dwordx4 v144, v[170:173], s[38:39] offset:256 sc1
	v_add_u32_e32 v145, 0x40000, v144
	global_load_dwordx4 v[174:177], v145, s[38:39] offset:256
	global_load_dwordx4 v[170:173], v145, s[18:19] offset:256
	s_add_u32 s18, s16, 0x10000
	s_addc_u32 s19, s17, 0
	s_add_u32 s38, s14, 0x10000
	s_addc_u32 s39, s15, 0
	s_waitcnt vmcnt(18)
; __device__ __forceinline__ u32x4 pack8(const f32x4 a, const f32x4 b) { u32x4 w; w.x = cvt_pk_bf16(a[0], a[1]); w.y = cvt_pk_bf16(a[2], a[3]); w.z = cvt_pk_bf16(b[0], b[1]); w.w = cvt_pk_bf16(b[2], b[3]); return w; }
;     __device__ __forceinline__ void operator()(const f32x4 (&acc)[2][2][4][2], const Unit& u, int wr, int wc, int fr, int fq) const {
;     ...
;             for (int m = 0; m < 4; ++m) { const size_t off = (size_t)(row0 + ai * HALF + m * 16) * 1024 + col0;
; #pragma unroll
;                 for (int bj = 0; bj < 2; ++bj) { const u32x4 gw = *(const u32x4*)(Gt + off + bj * HALF);
;                     f32x4 v0 = acc[ai][bj][m][0], v1 = acc[ai][bj][m][1];
;                     v0[0] *= bflo(gw.x); v0[1] *= bfhi(gw.x); v0[2] *= bflo(gw.y); v0[3] *= bfhi(gw.y);
;                     v1[0] *= bflo(gw.z); v1[1] *= bfhi(gw.z); v1[2] *= bflo(gw.w); v1[3] *= bfhi(gw.w);
;                     if (ADD) { const u32x4 pw = *(const u32x4*)(MG + off + bj * HALF);
;                         v0[0] += bflo(pw.x); v0[1] += bfhi(pw.x); v0[2] += bflo(pw.y); v0[3] += bfhi(pw.y);
;                         v1[0] += bflo(pw.z); v1[1] += bfhi(pw.z); v1[2] += bflo(pw.w); v1[3] += bfhi(pw.w); }
;                     *(u32x4*)(MG + off + bj * HALF) = pack8(v0, v1); }
;                 asm volatile("" ::: "memory"); }
	v_lshlrev_b32_e32 v145, 16, v178
	v_lshlrev_b32_e32 v149, 16, v182
	v_and_b32_e32 v178, 0xffff0000, v178
	v_and_b32_e32 v182, 0xffff0000, v182
	v_fmac_f32_e32 v149, v92, v145
	v_fmac_f32_e32 v182, v93, v178
	v_cvt_pk_bf16_f32 v178, v149, v182
	v_lshlrev_b32_e32 v145, 16, v179
	v_lshlrev_b32_e32 v149, 16, v183
	v_and_b32_e32 v179, 0xffff0000, v179
	v_and_b32_e32 v183, 0xffff0000, v183
	v_fmac_f32_e32 v149, v94, v145
	v_fmac_f32_e32 v183, v95, v179
	v_cvt_pk_bf16_f32 v179, v149, v183
	v_lshlrev_b32_e32 v145, 16, v180
	v_lshlrev_b32_e32 v149, 16, v184
	v_and_b32_e32 v180, 0xffff0000, v180
	v_and_b32_e32 v184, 0xffff0000, v184
	v_fmac_f32_e32 v149, v88, v145
	v_fmac_f32_e32 v184, v89, v180
	v_cvt_pk_bf16_f32 v180, v149, v184
	v_lshlrev_b32_e32 v145, 16, v181
	v_lshlrev_b32_e32 v149, 16, v185
	v_and_b32_e32 v181, 0xffff0000, v181
	v_and_b32_e32 v185, 0xffff0000, v185
	v_fmac_f32_e32 v149, v90, v145
	v_fmac_f32_e32 v185, v91, v181
	v_cvt_pk_bf16_f32 v181, v149, v185
	global_store_dwordx4 v144, v[178:181], s[38:39] sc1
	v_add_u32_e32 v145, 0x40000, v144
	global_load_dwordx4 v[182:185], v145, s[38:39]
	global_load_dwordx4 v[178:181], v145, s[18:19]
	s_waitcnt vmcnt(19)
	v_lshlrev_b32_e32 v145, 16, v194
	v_lshlrev_b32_e32 v149, 16, v198
	v_and_b32_e32 v194, 0xffff0000, v194
	v_and_b32_e32 v198, 0xffff0000, v198
	v_fmac_f32_e32 v149, v84, v145
	v_fmac_f32_e32 v198, v85, v194
	v_cvt_pk_bf16_f32 v194, v149, v198
	v_lshlrev_b32_e32 v145, 16, v195
	v_lshlrev_b32_e32 v149, 16, v199
	v_and_b32_e32 v195, 0xffff0000, v195
	v_and_b32_e32 v199, 0xffff0000, v199
	v_fmac_f32_e32 v149, v86, v145
	v_fmac_f32_e32 v199, v87, v195
	v_cvt_pk_bf16_f32 v195, v149, v199
	v_lshlrev_b32_e32 v145, 16, v196
	v_lshlrev_b32_e32 v149, 16, v200
	v_and_b32_e32 v196, 0xffff0000, v196
	v_and_b32_e32 v200, 0xffff0000, v200
	v_fmac_f32_e32 v149, v80, v145
	v_fmac_f32_e32 v200, v81, v196
	v_cvt_pk_bf16_f32 v196, v149, v200
	v_lshlrev_b32_e32 v145, 16, v197
	v_lshlrev_b32_e32 v149, 16, v201
	v_and_b32_e32 v197, 0xffff0000, v197
	v_and_b32_e32 v201, 0xffff0000, v201
	v_fmac_f32_e32 v149, v82, v145
	v_fmac_f32_e32 v201, v83, v197
	v_cvt_pk_bf16_f32 v197, v149, v201
	global_store_dwordx4 v144, v[194:197], s[38:39] offset:256 sc1
	v_add_u32_e32 v145, 0x40000, v144
	global_load_dwordx4 v[198:201], v145, s[38:39] offset:256
	global_load_dwordx4 v[194:197], v145, s[18:19] offset:256
	s_add_u32 s18, s16, 0x18000
	s_addc_u32 s19, s17, 0
	s_add_u32 s38, s14, 0x18000
	s_addc_u32 s39, s15, 0
	s_waitcnt vmcnt(20)
	v_lshlrev_b32_e32 v145, 16, v202
	v_lshlrev_b32_e32 v149, 16, v210
	v_and_b32_e32 v202, 0xffff0000, v202
	v_and_b32_e32 v210, 0xffff0000, v210
	v_fmac_f32_e32 v149, v76, v145
	v_fmac_f32_e32 v210, v77, v202
	v_cvt_pk_bf16_f32 v202, v149, v210
	v_lshlrev_b32_e32 v145, 16, v203
	v_lshlrev_b32_e32 v149, 16, v211
	v_and_b32_e32 v203, 0xffff0000, v203
	v_and_b32_e32 v211, 0xffff0000, v211
	v_fmac_f32_e32 v149, v78, v145
	v_fmac_f32_e32 v211, v79, v203
	v_cvt_pk_bf16_f32 v203, v149, v211
	v_lshlrev_b32_e32 v145, 16, v204
	v_lshlrev_b32_e32 v149, 16, v212
	v_and_b32_e32 v204, 0xffff0000, v204
	v_and_b32_e32 v212, 0xffff0000, v212
	v_fmac_f32_e32 v149, v72, v145
	v_fmac_f32_e32 v212, v73, v204
	v_cvt_pk_bf16_f32 v204, v149, v212
	v_lshlrev_b32_e32 v145, 16, v205
	v_lshlrev_b32_e32 v149, 16, v213
	v_and_b32_e32 v205, 0xffff0000, v205
	v_and_b32_e32 v213, 0xffff0000, v213
	v_fmac_f32_e32 v149, v74, v145
	v_fmac_f32_e32 v213, v75, v205
	v_cvt_pk_bf16_f32 v205, v149, v213
	global_store_dwordx4 v144, v[202:205], s[38:39] sc1
	v_add_u32_e32 v145, 0x40000, v144
	global_load_dwordx4 v[210:213], v145, s[38:39]
	global_load_dwordx4 v[202:205], v145, s[18:19]
	s_waitcnt vmcnt(21)
	v_lshlrev_b32_e32 v145, 16, v214
	v_lshlrev_b32_e32 v149, 16, v218
	v_and_b32_e32 v214, 0xffff0000, v214
	v_and_b32_e32 v218, 0xffff0000, v218
	v_fmac_f32_e32 v149, v68, v145
	v_fmac_f32_e32 v218, v69, v214
	v_cvt_pk_bf16_f32 v214, v149, v218
	v_lshlrev_b32_e32 v145, 16, v215
	v_lshlrev_b32_e32 v149, 16, v219
	v_and_b32_e32 v215, 0xffff0000, v215
	v_and_b32_e32 v219, 0xffff0000, v219
	v_fmac_f32_e32 v149, v70, v145
	v_fmac_f32_e32 v219, v71, v215
	v_cvt_pk_bf16_f32 v215, v149, v219
	v_lshlrev_b32_e32 v145, 16, v216
	v_lshlrev_b32_e32 v149, 16, v220
	v_and_b32_e32 v216, 0xffff0000, v216
	v_and_b32_e32 v220, 0xffff0000, v220
	v_fmac_f32_e32 v149, v64, v145
	v_fmac_f32_e32 v220, v65, v216
	v_cvt_pk_bf16_f32 v216, v149, v220
	v_lshlrev_b32_e32 v145, 16, v217
	v_lshlrev_b32_e32 v149, 16, v221
	v_and_b32_e32 v217, 0xffff0000, v217
	v_and_b32_e32 v221, 0xffff0000, v221
	v_fmac_f32_e32 v149, v66, v145
	v_fmac_f32_e32 v221, v67, v217
	v_cvt_pk_bf16_f32 v217, v149, v221
	global_store_dwordx4 v144, v[214:217], s[38:39] offset:256 sc1
	v_add_u32_e32 v145, 0x40000, v144
	global_load_dwordx4 v[218:221], v145, s[38:39] offset:256
	global_load_dwordx4 v[214:217], v145, s[18:19] offset:256
	s_mov_b64 s[18:19], s[16:17]
	s_mov_b64 s[38:39], s[14:15]
	s_waitcnt vmcnt(21)
	v_lshlrev_b32_e32 v145, 16, v140
	v_lshlrev_b32_e32 v149, 16, v150
	v_and_b32_e32 v140, 0xffff0000, v140
	v_and_b32_e32 v150, 0xffff0000, v150
	v_fmac_f32_e32 v149, v60, v145
	v_fmac_f32_e32 v150, v61, v140
	v_cvt_pk_bf16_f32 v140, v149, v150
	v_lshlrev_b32_e32 v145, 16, v141
	v_lshlrev_b32_e32 v149, 16, v151
	v_and_b32_e32 v141, 0xffff0000, v141
	v_and_b32_e32 v151, 0xffff0000, v151
	v_fmac_f32_e32 v149, v62, v145
	v_fmac_f32_e32 v151, v63, v141
	v_cvt_pk_bf16_f32 v141, v149, v151
	v_lshlrev_b32_e32 v145, 16, v142
	v_lshlrev_b32_e32 v149, 16, v152
	v_and_b32_e32 v142, 0xffff0000, v142
	v_and_b32_e32 v152, 0xffff0000, v152
	v_fmac_f32_e32 v149, v56, v145
	v_fmac_f32_e32 v152, v57, v142
	v_cvt_pk_bf16_f32 v142, v149, v152
	v_lshlrev_b32_e32 v145, 16, v143
	v_lshlrev_b32_e32 v149, 16, v153
	v_and_b32_e32 v143, 0xffff0000, v143
	v_and_b32_e32 v153, 0xffff0000, v153
	v_fmac_f32_e32 v149, v58, v145
	v_fmac_f32_e32 v153, v59, v143
	v_cvt_pk_bf16_f32 v143, v149, v153
	v_add_u32_e32 v145, 0x40000, v144
	global_store_dwordx4 v145, v[140:143], s[38:39] sc1
	s_waitcnt vmcnt(19)
; __device__ __forceinline__ u32x4 pack8(const f32x4 a, const f32x4 b) { u32x4 w; w.x = cvt_pk_bf16(a[0], a[1]); w.y = cvt_pk_bf16(a[2], a[3]); w.z = cvt_pk_bf16(b[0], b[1]); w.w = cvt_pk_bf16(b[2], b[3]); return w; }
;     __device__ __forceinline__ void operator()(const f32x4 (&acc)[2][2][4][2], const Unit& u, int wr, int wc, int fr, int fq) const {
;     ...
;             for (int m = 0; m < 4; ++m) { const size_t off = (size_t)(row0 + ai * HALF + m * 16) * 1024 + col0;
; #pragma unroll
;                 for (int bj = 0; bj < 2; ++bj) { const u32x4 gw = *(const u32x4*)(Gt + off + bj * HALF);
;                     f32x4 v0 = acc[ai][bj][m][0], v1 = acc[ai][bj][m][1];
;                     v0[0] *= bflo(gw.x); v0[1] *= bfhi(gw.x); v0[2] *= bflo(gw.y); v0[3] *= bfhi(gw.y);
;                     v1[0] *= bflo(gw.z); v1[1] *= bfhi(gw.z); v1[2] *= bflo(gw.w); v1[3] *= bfhi(gw.w);
;                     if (ADD) { const u32x4 pw = *(const u32x4*)(MG + off + bj * HALF);
;                         v0[0] += bflo(pw.x); v0[1] += bfhi(pw.x); v0[2] += bflo(pw.y); v0[3] += bfhi(pw.y);
;                         v1[0] += bflo(pw.z); v1[1] += bfhi(pw.z); v1[2] += bflo(pw.w); v1[3] += bfhi(pw.w); }
;                     *(u32x4*)(MG + off + bj * HALF) = pack8(v0, v1); }
;                 asm volatile("" ::: "memory"); }
	v_lshlrev_b32_e32 v145, 16, v154
	v_lshlrev_b32_e32 v149, 16, v158
	v_and_b32_e32 v154, 0xffff0000, v154
	v_and_b32_e32 v158, 0xffff0000, v158
	v_fmac_f32_e32 v149, v52, v145
	v_fmac_f32_e32 v158, v53, v154
	v_cvt_pk_bf16_f32 v154, v149, v158
	v_lshlrev_b32_e32 v145, 16, v155
	v_lshlrev_b32_e32 v149, 16, v159
	v_and_b32_e32 v155, 0xffff0000, v155
	v_and_b32_e32 v159, 0xffff0000, v159
	v_fmac_f32_e32 v149, v54, v145
	v_fmac_f32_e32 v159, v55, v155
	v_cvt_pk_bf16_f32 v155, v149, v159
	v_lshlrev_b32_e32 v145, 16, v156
	v_lshlrev_b32_e32 v149, 16, v160
	v_and_b32_e32 v156, 0xffff0000, v156
	v_and_b32_e32 v160, 0xffff0000, v160
	v_fmac_f32_e32 v149, v48, v145
	v_fmac_f32_e32 v160, v49, v156
	v_cvt_pk_bf16_f32 v156, v149, v160
	v_lshlrev_b32_e32 v145, 16, v157
	v_lshlrev_b32_e32 v149, 16, v161
	v_and_b32_e32 v157, 0xffff0000, v157
	v_and_b32_e32 v161, 0xffff0000, v161
	v_fmac_f32_e32 v149, v50, v145
	v_fmac_f32_e32 v161, v51, v157
	v_cvt_pk_bf16_f32 v157, v149, v161
	v_add_u32_e32 v145, 0x40000, v144
	global_store_dwordx4 v145, v[154:157], s[38:39] offset:256 sc1
	s_add_u32 s18, s16, 0x8000
	s_addc_u32 s19, s17, 0
	s_add_u32 s38, s14, 0x8000
	s_addc_u32 s39, s15, 0
	s_waitcnt vmcnt(17)
	v_lshlrev_b32_e32 v145, 16, v162
	v_lshlrev_b32_e32 v149, 16, v166
	v_and_b32_e32 v162, 0xffff0000, v162
	v_and_b32_e32 v166, 0xffff0000, v166
	v_fmac_f32_e32 v149, v44, v145
	v_fmac_f32_e32 v166, v45, v162
	v_cvt_pk_bf16_f32 v162, v149, v166
	v_lshlrev_b32_e32 v145, 16, v163
	v_lshlrev_b32_e32 v149, 16, v167
	v_and_b32_e32 v163, 0xffff0000, v163
	v_and_b32_e32 v167, 0xffff0000, v167
	v_fmac_f32_e32 v149, v46, v145
	v_fmac_f32_e32 v167, v47, v163
	v_cvt_pk_bf16_f32 v163, v149, v167
	v_lshlrev_b32_e32 v145, 16, v164
	v_lshlrev_b32_e32 v149, 16, v168
	v_and_b32_e32 v164, 0xffff0000, v164
	v_and_b32_e32 v168, 0xffff0000, v168
	v_fmac_f32_e32 v149, v40, v145
	v_fmac_f32_e32 v168, v41, v164
	v_cvt_pk_bf16_f32 v164, v149, v168
	v_lshlrev_b32_e32 v145, 16, v165
	v_lshlrev_b32_e32 v149, 16, v169
	v_and_b32_e32 v165, 0xffff0000, v165
	v_and_b32_e32 v169, 0xffff0000, v169
	v_fmac_f32_e32 v149, v42, v145
	v_fmac_f32_e32 v169, v43, v165
	v_cvt_pk_bf16_f32 v165, v149, v169
	v_add_u32_e32 v145, 0x40000, v144
	global_store_dwordx4 v145, v[162:165], s[38:39] sc1
	s_waitcnt vmcnt(15)
	v_lshlrev_b32_e32 v145, 16, v170
	v_lshlrev_b32_e32 v149, 16, v174
	v_and_b32_e32 v170, 0xffff0000, v170
	v_and_b32_e32 v174, 0xffff0000, v174
	v_fmac_f32_e32 v149, v36, v145
	v_fmac_f32_e32 v174, v37, v170
	v_cvt_pk_bf16_f32 v170, v149, v174
	v_lshlrev_b32_e32 v145, 16, v171
	v_lshlrev_b32_e32 v149, 16, v175
	v_and_b32_e32 v171, 0xffff0000, v171
	v_and_b32_e32 v175, 0xffff0000, v175
	v_fmac_f32_e32 v149, v38, v145
	v_fmac_f32_e32 v175, v39, v171
	v_cvt_pk_bf16_f32 v171, v149, v175
	v_lshlrev_b32_e32 v145, 16, v172
	v_lshlrev_b32_e32 v149, 16, v176
	v_and_b32_e32 v172, 0xffff0000, v172
	v_and_b32_e32 v176, 0xffff0000, v176
	v_fmac_f32_e32 v149, v32, v145
	v_fmac_f32_e32 v176, v33, v172
	v_cvt_pk_bf16_f32 v172, v149, v176
	v_lshlrev_b32_e32 v145, 16, v173
	v_lshlrev_b32_e32 v149, 16, v177
	v_and_b32_e32 v173, 0xffff0000, v173
	v_and_b32_e32 v177, 0xffff0000, v177
	v_fmac_f32_e32 v149, v34, v145
	v_fmac_f32_e32 v177, v35, v173
	v_cvt_pk_bf16_f32 v173, v149, v177
	v_add_u32_e32 v145, 0x40000, v144
	global_store_dwordx4 v145, v[170:173], s[38:39] offset:256 sc1
	s_add_u32 s18, s16, 0x10000
	s_addc_u32 s19, s17, 0
	s_add_u32 s38, s14, 0x10000
	s_addc_u32 s39, s15, 0
	s_waitcnt vmcnt(13)
; __device__ __forceinline__ u32x4 pack8(const f32x4 a, const f32x4 b) { u32x4 w; w.x = cvt_pk_bf16(a[0], a[1]); w.y = cvt_pk_bf16(a[2], a[3]); w.z = cvt_pk_bf16(b[0], b[1]); w.w = cvt_pk_bf16(b[2], b[3]); return w; }
;     __device__ __forceinline__ void operator()(const f32x4 (&acc)[2][2][4][2], const Unit& u, int wr, int wc, int fr, int fq) const {
;     ...
;             for (int m = 0; m < 4; ++m) { const size_t off = (size_t)(row0 + ai * HALF + m * 16) * 1024 + col0;
; #pragma unroll
;                 for (int bj = 0; bj < 2; ++bj) { const u32x4 gw = *(const u32x4*)(Gt + off + bj * HALF);
;                     f32x4 v0 = acc[ai][bj][m][0], v1 = acc[ai][bj][m][1];
;                     v0[0] *= bflo(gw.x); v0[1] *= bfhi(gw.x); v0[2] *= bflo(gw.y); v0[3] *= bfhi(gw.y);
;                     v1[0] *= bflo(gw.z); v1[1] *= bfhi(gw.z); v1[2] *= bflo(gw.w); v1[3] *= bfhi(gw.w);
;                     if (ADD) { const u32x4 pw = *(const u32x4*)(MG + off + bj * HALF);
;                         v0[0] += bflo(pw.x); v0[1] += bfhi(pw.x); v0[2] += bflo(pw.y); v0[3] += bfhi(pw.y);
;                         v1[0] += bflo(pw.z); v1[1] += bfhi(pw.z); v1[2] += bflo(pw.w); v1[3] += bfhi(pw.w); }
;                     *(u32x4*)(MG + off + bj * HALF) = pack8(v0, v1); }
;                 asm volatile("" ::: "memory"); }
	v_lshlrev_b32_e32 v145, 16, v178
	v_lshlrev_b32_e32 v149, 16, v182
	v_and_b32_e32 v178, 0xffff0000, v178
	v_and_b32_e32 v182, 0xffff0000, v182
	v_fmac_f32_e32 v149, v28, v145
	v_fmac_f32_e32 v182, v29, v178
	v_cvt_pk_bf16_f32 v178, v149, v182
	v_lshlrev_b32_e32 v145, 16, v179
	v_lshlrev_b32_e32 v149, 16, v183
	v_and_b32_e32 v179, 0xffff0000, v179
	v_and_b32_e32 v183, 0xffff0000, v183
	v_fmac_f32_e32 v149, v30, v145
	v_fmac_f32_e32 v183, v31, v179
	v_cvt_pk_bf16_f32 v179, v149, v183
	v_lshlrev_b32_e32 v145, 16, v180
	v_lshlrev_b32_e32 v149, 16, v184
	v_and_b32_e32 v180, 0xffff0000, v180
	v_and_b32_e32 v184, 0xffff0000, v184
	v_fmac_f32_e32 v149, v24, v145
	v_fmac_f32_e32 v184, v25, v180
	v_cvt_pk_bf16_f32 v180, v149, v184
	v_lshlrev_b32_e32 v145, 16, v181
	v_lshlrev_b32_e32 v149, 16, v185
	v_and_b32_e32 v181, 0xffff0000, v181
	v_and_b32_e32 v185, 0xffff0000, v185
	v_fmac_f32_e32 v149, v26, v145
	v_fmac_f32_e32 v185, v27, v181
	v_cvt_pk_bf16_f32 v181, v149, v185
	v_add_u32_e32 v145, 0x40000, v144
	global_store_dwordx4 v145, v[178:181], s[38:39] sc1
	s_waitcnt vmcnt(11)
	v_lshlrev_b32_e32 v145, 16, v194
	v_lshlrev_b32_e32 v149, 16, v198
	v_and_b32_e32 v194, 0xffff0000, v194
	v_and_b32_e32 v198, 0xffff0000, v198
	v_fmac_f32_e32 v149, v20, v145
	v_fmac_f32_e32 v198, v21, v194
	v_cvt_pk_bf16_f32 v194, v149, v198
	v_lshlrev_b32_e32 v145, 16, v195
	v_lshlrev_b32_e32 v149, 16, v199
	v_and_b32_e32 v195, 0xffff0000, v195
	v_and_b32_e32 v199, 0xffff0000, v199
	v_fmac_f32_e32 v149, v22, v145
	v_fmac_f32_e32 v199, v23, v195
	v_cvt_pk_bf16_f32 v195, v149, v199
	v_lshlrev_b32_e32 v145, 16, v196
	v_lshlrev_b32_e32 v149, 16, v200
	v_and_b32_e32 v196, 0xffff0000, v196
	v_and_b32_e32 v200, 0xffff0000, v200
	v_fmac_f32_e32 v149, v16, v145
	v_fmac_f32_e32 v200, v17, v196
	v_cvt_pk_bf16_f32 v196, v149, v200
	v_lshlrev_b32_e32 v145, 16, v197
	v_lshlrev_b32_e32 v149, 16, v201
	v_and_b32_e32 v197, 0xffff0000, v197
	v_and_b32_e32 v201, 0xffff0000, v201
	v_fmac_f32_e32 v149, v18, v145
	v_fmac_f32_e32 v201, v19, v197
	v_cvt_pk_bf16_f32 v197, v149, v201
	v_add_u32_e32 v145, 0x40000, v144
	global_store_dwordx4 v145, v[194:197], s[38:39] offset:256 sc1
	s_add_u32 s18, s16, 0x18000
	s_addc_u32 s19, s17, 0
	s_add_u32 s38, s14, 0x18000
	s_addc_u32 s39, s15, 0
	s_waitcnt vmcnt(9)
	v_lshlrev_b32_e32 v145, 16, v202
	v_lshlrev_b32_e32 v149, 16, v210
	v_and_b32_e32 v202, 0xffff0000, v202
	v_and_b32_e32 v210, 0xffff0000, v210
	v_fmac_f32_e32 v149, v12, v145
	v_fmac_f32_e32 v210, v13, v202
	v_cvt_pk_bf16_f32 v202, v149, v210
	v_lshlrev_b32_e32 v145, 16, v203
	v_lshlrev_b32_e32 v149, 16, v211
	v_and_b32_e32 v203, 0xffff0000, v203
	v_and_b32_e32 v211, 0xffff0000, v211
	v_fmac_f32_e32 v149, v14, v145
	v_fmac_f32_e32 v211, v15, v203
	v_cvt_pk_bf16_f32 v203, v149, v211
	v_lshlrev_b32_e32 v145, 16, v204
	v_lshlrev_b32_e32 v149, 16, v212
	v_and_b32_e32 v204, 0xffff0000, v204
	v_and_b32_e32 v212, 0xffff0000, v212
	v_fmac_f32_e32 v149, v8, v145
	v_fmac_f32_e32 v212, v9, v204
	v_cvt_pk_bf16_f32 v204, v149, v212
	v_lshlrev_b32_e32 v145, 16, v205
	v_lshlrev_b32_e32 v149, 16, v213
	v_and_b32_e32 v205, 0xffff0000, v205
	v_and_b32_e32 v213, 0xffff0000, v213
	v_fmac_f32_e32 v149, v10, v145
	v_fmac_f32_e32 v213, v11, v205
	v_cvt_pk_bf16_f32 v205, v149, v213
	v_add_u32_e32 v145, 0x40000, v144
	global_store_dwordx4 v145, v[202:205], s[38:39] sc1
	s_waitcnt vmcnt(7)
	v_lshlrev_b32_e32 v145, 16, v214
	v_lshlrev_b32_e32 v149, 16, v218
	v_and_b32_e32 v214, 0xffff0000, v214
	v_and_b32_e32 v218, 0xffff0000, v218
	v_fmac_f32_e32 v149, v4, v145
	v_fmac_f32_e32 v218, v5, v214
	v_cvt_pk_bf16_f32 v214, v149, v218
	v_lshlrev_b32_e32 v145, 16, v215
	v_lshlrev_b32_e32 v149, 16, v219
	v_and_b32_e32 v215, 0xffff0000, v215
	v_and_b32_e32 v219, 0xffff0000, v219
	v_fmac_f32_e32 v149, v6, v145
	v_fmac_f32_e32 v219, v7, v215
	v_cvt_pk_bf16_f32 v215, v149, v219
	v_lshlrev_b32_e32 v145, 16, v216
	v_lshlrev_b32_e32 v149, 16, v220
	v_and_b32_e32 v216, 0xffff0000, v216
	v_and_b32_e32 v220, 0xffff0000, v220
	v_fmac_f32_e32 v149, v0, v145
	v_fmac_f32_e32 v220, v1, v216
	v_cvt_pk_bf16_f32 v216, v149, v220
	v_lshlrev_b32_e32 v145, 16, v217
	v_lshlrev_b32_e32 v149, 16, v221
	v_and_b32_e32 v217, 0xffff0000, v217
	v_and_b32_e32 v221, 0xffff0000, v221
	v_fmac_f32_e32 v149, v2, v145
	v_fmac_f32_e32 v221, v3, v217
	v_cvt_pk_bf16_f32 v217, v149, v221
	v_add_u32_e32 v145, 0x40000, v144
	global_store_dwordx4 v145, v[214:217], s[38:39] offset:256 sc1

; __device__ __forceinline__ void rms_row(const f32x4 (&v)[4], const float* g, int lane, float& rs, f32x4 (&y)[4]) {
;     float s = 0.f;
; #pragma unroll
;     for (int j = 0; j < 4; ++j) s += (v[j].x * v[j].x + v[j].y * v[j].y) + (v[j].z * v[j].z + v[j].w * v[j].w);
;     rs = __builtin_amdgcn_rsqf(wave_sum(s) * (1.f / DM) + EPS);
; #pragma unroll
;     for (int j = 0; j < 4; ++j) { const f32x4 gv = *((const f32x4*)g + lane + 64 * j); y[j] = v[j] * rs * gv; }
; }
; __device__ __forceinline__ void load_bf16_row(const bf16* row, int lane, f32x4 (&v)[4]) {
;     const u32x2* p = (const u32x2*)row + lane;
; #pragma unroll
;     for (int j = 0; j < 4; ++j) { const u32x2 w = p[64 * j]; v[j] = (f32x4){bflo(w.x), bfhi(w.x), bflo(w.y), bfhi(w.y)}; }
; template <int NSLICE> __device__ __forceinline__ void rms_phase(ArgP a, const float* g, bool final_out, int G) {
;     ...
;     for (int m = gw; m < R_META; m += 2 * NGW) {
;         const int m2 = m + NGW; const bool has2 = m2 < R_META;
;         f32x4 v[4], u[4];
;         load_bf16_row(H + (size_t)m * DM, lane, v); load_bf16_row(H + (size_t)(has2 ? m2 : m) * DM, lane, u);
;         float rs; f32x4 y[4];
;         rms_row(v, g, lane, rs, y);
;         if (!final_out) store_bf16_row(XN + (size_t)m * DM, lane, y);
;         else { float* o = a->out + O_YP + (size_t)m * DM;
; #pragma unroll
;             for (int j = 0; j < 4; ++j) *((f32x4*)o + lane + 64 * j) = y[j]; }
.LBB0_1317:
	v_ashrrev_i32_e32 v37, 31, v36
	v_lshlrev_b64 v[0:1], 11, v[36:37]
	v_lshl_add_u64 v[0:1], v[20:21], 0, v[0:1]
	global_load_dwordx2 v[2:3], v[0:1], off
	global_load_dwordx2 v[6:7], v[0:1], off offset:512
	global_load_dwordx2 v[10:11], v[0:1], off offset:1024
	s_nop 0
	global_load_dwordx2 v[0:1], v[0:1], off offset:1536
	v_add_u32_e32 v26, s38, v36
	s_movk_i32 s14, 0x4000
	v_cmp_gt_i32_e32 vcc, s14, v26
	s_waitcnt vmcnt(0)
	v_lshlrev_b32_e32 v39, 16, v0
	v_and_b32_e32 v15, 0xffff0000, v0
	v_cndmask_b32_e32 v0, v36, v26, vcc
	v_lshlrev_b32_e32 v12, 16, v1
	v_and_b32_e32 v13, 0xffff0000, v1
	v_ashrrev_i32_e32 v1, 31, v0
	v_lshlrev_b64 v[0:1], 11, v[0:1]
	v_lshl_add_u64 v[0:1], v[20:21], 0, v[0:1]
	global_load_dwordx2 v[32:33], v[0:1], off
	global_load_dwordx2 v[30:31], v[0:1], off offset:512
	global_load_dwordx2 v[28:29], v[0:1], off offset:1024
	global_load_dwordx2 v[34:35], v[0:1], off offset:1536
	v_lshlrev_b32_e32 v0, 16, v2
	v_and_b32_e32 v1, 0xffff0000, v2
	v_lshlrev_b32_e32 v2, 16, v3
	v_and_b32_e32 v3, 0xffff0000, v3
	v_mul_f32_e32 v4, v3, v3
	v_pk_fma_f32 v[48:49], v[2:3], v[2:3], v[4:5] op_sel_hi:[1,1,0]
	v_lshlrev_b32_e32 v5, 16, v7
	v_lshlrev_b32_e32 v4, 16, v6
	v_and_b32_e32 v7, 0xffff0000, v7
	v_and_b32_e32 v6, 0xffff0000, v6
	v_mul_f32_e32 v14, v1, v1
	v_pk_mul_f32 v[8:9], v[6:7], v[6:7]
	v_pk_fma_f32 v[52:53], v[0:1], v[0:1], v[14:15] op_sel_hi:[1,1,0]
	v_pk_fma_f32 v[50:51], v[4:5], v[4:5], v[8:9]
	v_mov_b32_e32 v38, v52
	v_mov_b32_e32 v54, v48
	v_mov_b32_e32 v55, v39
	v_and_b32_e32 v9, 0xffff0000, v10
	v_mul_f32_e32 v17, v15, v15
	v_pk_add_f32 v[48:49], v[52:53], v[48:49]
	v_pk_mul_f32 v[52:53], v[38:39], v[54:55]
	v_pk_add_f32 v[50:51], v[50:51], v[50:51] op_sel:[0,1] op_sel_hi:[1,0]
	v_lshlrev_b32_e32 v8, 16, v10
	v_lshlrev_b32_e32 v10, 16, v11
	v_and_b32_e32 v11, 0xffff0000, v11
	v_mov_b32_e32 v49, v53
	v_mov_b32_e32 v51, v17
	v_mul_f32_e32 v14, v9, v9
	v_pk_add_f32 v[48:49], v[48:49], v[50:51]
	v_pk_fma_f32 v[50:51], v[8:9], v[8:9], v[14:15] op_sel_hi:[1,1,0]
	v_mul_f32_e32 v14, v11, v11
	v_mul_f32_e32 v27, v12, v12
	v_mul_f32_e32 v47, v13, v13
	v_pk_fma_f32 v[52:53], v[10:11], v[10:11], v[14:15] op_sel_hi:[1,1,0]
	v_mov_b32_e32 v51, v27
	v_mov_b32_e32 v53, v47
	v_pk_add_f32 v[50:51], v[50:51], v[52:53]
	v_mov_b32_e32 v52, v4
	v_pk_add_f32 v[48:49], v[48:49], v[50:51]
	v_mov_b32_e32 v53, v6
	v_add_f32_e32 v14, v48, v49
	global_load_dwordx4 v[48:51], v[22:23], off
	ds_bpermute_b32 v17, v41, v14
	v_mov_b32_e32 v6, v5
	v_lshlrev_b64 v[36:37], 12, v[36:37]
	v_lshl_add_u64 v[36:37], v[24:25], 0, v[36:37]
	s_waitcnt lgkmcnt(0)
	v_add_f32_e32 v14, v14, v17
	ds_bpermute_b32 v17, v42, v14
	s_waitcnt lgkmcnt(0)
	v_add_f32_e32 v14, v14, v17
	ds_bpermute_b32 v17, v43, v14
	s_waitcnt lgkmcnt(0)
	v_add_f32_e32 v14, v14, v17
	ds_bpermute_b32 v17, v44, v14
	s_waitcnt lgkmcnt(0)
	v_add_f32_e32 v14, v14, v17
	ds_bpermute_b32 v17, v45, v14
	s_waitcnt lgkmcnt(0)
	v_add_f32_e32 v14, v14, v17
	ds_bpermute_b32 v17, v46, v14
	s_waitcnt lgkmcnt(0)
	v_add_f32_e32 v14, v14, v17
	v_fmamk_f32 v14, v14, 0x3a800000, v207
	v_rsq_f32_e32 v38, v14
	v_mov_b32_e32 v14, v39
	v_pk_mul_f32 v[0:1], v[38:39], v[0:1] op_sel_hi:[0,1]
	v_pk_mul_f32 v[2:3], v[38:39], v[2:3] op_sel_hi:[0,1]
	v_pk_mul_f32 v[52:53], v[38:39], v[52:53] op_sel_hi:[0,1]
	v_pk_mul_f32 v[4:5], v[38:39], v[6:7] op_sel_hi:[0,1]
	v_pk_mul_f32 v[8:9], v[38:39], v[8:9] op_sel_hi:[0,1]
	v_pk_mul_f32 v[10:11], v[38:39], v[10:11] op_sel_hi:[0,1]
	v_pk_mul_f32 v[12:13], v[38:39], v[12:13] op_sel_hi:[0,1]
	s_waitcnt vmcnt(0)
	v_pk_mul_f32 v[2:3], v[50:51], v[2:3]
	v_pk_mul_f32 v[0:1], v[48:49], v[0:1]
	global_load_dwordx4 v[48:51], v[22:23], off offset:1024
	s_waitcnt vmcnt(0)
	v_pk_mul_f32 v[6:7], v[50:51], v[4:5]
	v_pk_mul_f32 v[4:5], v[48:49], v[52:53]
	global_load_dwordx4 v[48:51], v[22:23], off offset:2048
	v_pk_mul_f32 v[52:53], v[38:39], v[14:15] op_sel_hi:[0,1]
	s_waitcnt vmcnt(0)
	v_pk_mul_f32 v[10:11], v[50:51], v[10:11]
	v_pk_mul_f32 v[8:9], v[48:49], v[8:9]
	global_load_dwordx4 v[48:51], v[22:23], off offset:3072
	s_waitcnt vmcnt(0)
	v_pk_mul_f32 v[14:15], v[50:51], v[12:13]
	v_pk_mul_f32 v[12:13], v[48:49], v[52:53]
	global_store_dwordx4 v[36:37], v[0:3], off sc1
	global_store_dwordx4 v[36:37], v[4:7], off offset:1024 sc1
	global_store_dwordx4 v[36:37], v[8:11], off offset:2048 sc1
	global_store_dwordx4 v[36:37], v[12:15], off offset:3072 sc1
	s_and_saveexec_b64 s[14:15], vcc
	s_cbranch_execz .LBB0_1316
; __device__ __forceinline__ void rms_row(const f32x4 (&v)[4], const float* g, int lane, float& rs, f32x4 (&y)[4]) {
;     float s = 0.f;
; #pragma unroll
;     for (int j = 0; j < 4; ++j) s += (v[j].x * v[j].x + v[j].y * v[j].y) + (v[j].z * v[j].z + v[j].w * v[j].w);
;     rs = __builtin_amdgcn_rsqf(wave_sum(s) * (1.f / DM) + EPS);
; #pragma unroll
;     for (int j = 0; j < 4; ++j) { const f32x4 gv = *((const f32x4*)g + lane + 64 * j); y[j] = v[j] * rs * gv; }
; }
; __device__ __forceinline__ void load_bf16_row(const bf16* row, int lane, f32x4 (&v)[4]) {
;     const u32x2* p = (const u32x2*)row + lane;
; #pragma unroll
;     for (int j = 0; j < 4; ++j) { const u32x2 w = p[64 * j]; v[j] = (f32x4){bflo(w.x), bfhi(w.x), bflo(w.y), bfhi(w.y)}; }
; template <int NSLICE> __device__ __forceinline__ void rms_phase(ArgP a, const float* g, bool final_out, int G) {
;     ...
;         if (has2) {
;             rms_row(u, g, lane, rs, y);
;             if (!final_out) store_bf16_row(XN + (size_t)m2 * DM, lane, y);
;             else { float* o = a->out + O_YP + (size_t)m2 * DM;
; #pragma unroll
;                 for (int j = 0; j < 4; ++j) *((f32x4*)o + lane + 64 * j) = y[j]; }
;         }
	v_lshlrev_b32_e32 v37, 16, v34
	v_and_b32_e32 v15, 0xffff0000, v34
	v_lshlrev_b32_e32 v12, 16, v35
	v_and_b32_e32 v13, 0xffff0000, v35
	v_lshlrev_b32_e32 v34, 16, v32
	v_and_b32_e32 v35, 0xffff0000, v32
	v_lshlrev_b32_e32 v32, 16, v33
	v_and_b32_e32 v33, 0xffff0000, v33
	v_mul_f32_e32 v0, v33, v33
	v_and_b32_e32 v7, 0xffff0000, v31
	v_and_b32_e32 v6, 0xffff0000, v30
	v_mul_f32_e32 v14, v35, v35
	v_pk_fma_f32 v[0:1], v[32:33], v[32:33], v[0:1] op_sel_hi:[1,1,0]
	v_lshlrev_b32_e32 v5, 16, v31
	v_lshlrev_b32_e32 v4, 16, v30
	v_pk_mul_f32 v[2:3], v[6:7], v[6:7]
	v_lshlrev_b32_e32 v8, 16, v28
	v_and_b32_e32 v9, 0xffff0000, v28
	v_lshlrev_b32_e32 v10, 16, v29
	v_and_b32_e32 v11, 0xffff0000, v29
	v_pk_fma_f32 v[28:29], v[34:35], v[34:35], v[14:15] op_sel_hi:[1,1,0]
	v_pk_fma_f32 v[2:3], v[4:5], v[4:5], v[2:3]
	v_mov_b32_e32 v36, v28
	v_mov_b32_e32 v30, v0
	v_mov_b32_e32 v31, v37
	v_mul_f32_e32 v17, v15, v15
	v_pk_add_f32 v[0:1], v[28:29], v[0:1]
	v_pk_mul_f32 v[28:29], v[36:37], v[30:31]
	v_pk_add_f32 v[2:3], v[2:3], v[2:3] op_sel:[0,1] op_sel_hi:[1,0]
	v_mov_b32_e32 v1, v29
	v_mov_b32_e32 v3, v17
	v_pk_add_f32 v[0:1], v[0:1], v[2:3]
	v_mul_f32_e32 v2, v9, v9
	v_mul_f32_e32 v14, v11, v11
	v_mul_f32_e32 v27, v12, v12
	v_mul_f32_e32 v38, v13, v13
	v_pk_fma_f32 v[2:3], v[8:9], v[8:9], v[2:3] op_sel_hi:[1,1,0]
	v_pk_fma_f32 v[28:29], v[10:11], v[10:11], v[14:15] op_sel_hi:[1,1,0]
	v_mov_b32_e32 v3, v27
	v_mov_b32_e32 v29, v38
	v_pk_add_f32 v[2:3], v[2:3], v[28:29]
	v_mov_b32_e32 v14, v37
	v_pk_add_f32 v[0:1], v[0:1], v[2:3]
	v_ashrrev_i32_e32 v27, 31, v26
	v_add_f32_e32 v0, v0, v1
	ds_bpermute_b32 v1, v41, v0
	s_waitcnt lgkmcnt(0)
	v_add_f32_e32 v0, v0, v1
	ds_bpermute_b32 v1, v42, v0
	s_waitcnt lgkmcnt(0)
	v_add_f32_e32 v0, v0, v1
	ds_bpermute_b32 v1, v43, v0
	s_waitcnt lgkmcnt(0)
	v_add_f32_e32 v0, v0, v1
	ds_bpermute_b32 v1, v44, v0
	s_waitcnt lgkmcnt(0)
	v_add_f32_e32 v0, v0, v1
	ds_bpermute_b32 v1, v45, v0
	s_waitcnt lgkmcnt(0)
	v_add_f32_e32 v0, v0, v1
	ds_bpermute_b32 v1, v46, v0
	s_waitcnt lgkmcnt(0)
	v_add_f32_e32 v0, v0, v1
	v_fmamk_f32 v0, v0, 0x3a800000, v207
	v_rsq_f32_e32 v28, v0
	global_load_dwordx4 v[0:3], v[22:23], off
	v_pk_mul_f32 v[30:31], v[28:29], v[34:35] op_sel_hi:[0,1]
	v_pk_mul_f32 v[32:33], v[28:29], v[32:33] op_sel_hi:[0,1]
	v_mov_b32_e32 v34, v4
	v_mov_b32_e32 v35, v6
	v_mov_b32_e32 v6, v5
	v_pk_mul_f32 v[34:35], v[28:29], v[34:35] op_sel_hi:[0,1]
	v_pk_mul_f32 v[4:5], v[28:29], v[6:7] op_sel_hi:[0,1]
	v_pk_mul_f32 v[8:9], v[28:29], v[8:9] op_sel_hi:[0,1]
	v_pk_mul_f32 v[10:11], v[28:29], v[10:11] op_sel_hi:[0,1]
	v_pk_mul_f32 v[12:13], v[28:29], v[12:13] op_sel_hi:[0,1]
	s_waitcnt vmcnt(0)
	v_pk_mul_f32 v[2:3], v[2:3], v[32:33]
	v_pk_mul_f32 v[0:1], v[0:1], v[30:31]
	global_load_dwordx4 v[30:33], v[22:23], off offset:1024
	s_waitcnt vmcnt(0)
	v_pk_mul_f32 v[6:7], v[32:33], v[4:5]
	v_pk_mul_f32 v[4:5], v[30:31], v[34:35]
	global_load_dwordx4 v[30:33], v[22:23], off offset:2048
	v_pk_mul_f32 v[34:35], v[28:29], v[14:15] op_sel_hi:[0,1]
	v_lshlrev_b64 v[28:29], 12, v[26:27]
	v_lshl_add_u64 v[28:29], v[24:25], 0, v[28:29]
	s_waitcnt vmcnt(0)
	v_pk_mul_f32 v[10:11], v[32:33], v[10:11]
	v_pk_mul_f32 v[8:9], v[30:31], v[8:9]
	global_load_dwordx4 v[30:33], v[22:23], off offset:3072
	s_waitcnt vmcnt(0)
	v_pk_mul_f32 v[14:15], v[32:33], v[12:13]
	v_pk_mul_f32 v[12:13], v[30:31], v[34:35]
	global_store_dwordx4 v[28:29], v[0:3], off sc1
	global_store_dwordx4 v[28:29], v[4:7], off offset:1024 sc1
	global_store_dwordx4 v[28:29], v[8:11], off offset:2048 sc1
	global_store_dwordx4 v[28:29], v[12:15], off offset:3072 sc1
	s_branch .LBB0_1316

; __device__ __forceinline__ void load_bf16_row(const bf16* row, int lane, f32x4 (&v)[4]) {
;     const u32x2* p = (const u32x2*)row + lane;
; #pragma unroll
;     for (int j = 0; j < 4; ++j) { const u32x2 w = p[64 * j]; v[j] = (f32x4){bflo(w.x), bfhi(w.x), bflo(w.y), bfhi(w.y)}; }
; }
; template <int NSLICE> __device__ __forceinline__ void rms_phase(ArgP a, const float* g, bool final_out, int G) {
;     ...
;     for (int t = (NGW - 1 - gw); t < M_REAL - R_META; t += NGW) {
;         const int m = R_META + t;
;         if (final_out && m < R_SAMP) continue;
;         f32x4 v[4]; load_bf16_row(H + (size_t)m * DM, lane, v);
;         const bf16* PART = (const bf16*)(a->ws + WS_P + 6 * ROWBUF) + (size_t)t * DM;
; #pragma unroll
;         for (int sl = 0; sl < NSLICE; ++sl) {
;             f32x4 pv[4]; load_bf16_row(PART + (size_t)sl * (MP - R_META) * DM, lane, pv);
; #pragma unroll
;             for (int j = 0; j < 4; ++j) v[j] = v[j] + pv[j];
;         }
.LBB0_1328:
	v_add_u32_e32 v0, 0xffffc000, v188
	s_movk_i32 s8, 0x7f
	v_cmp_lt_i32_e32 vcc, s8, v0
	s_and_saveexec_b64 s[8:9], vcc
	s_cbranch_execz .LBB0_1327
	v_mov_b32_e32 v1, v189
	v_lshlrev_b64 v[2:3], 11, v[188:189]
	v_lshlrev_b64 v[0:1], 11, v[0:1]
	v_lshl_add_u64 v[2:3], v[12:13], 0, v[2:3]
	v_lshl_add_u64 v[0:1], v[14:15], 0, v[0:1]
	global_load_dwordx2 v[4:5], v[2:3], off
	global_load_dwordx2 v[8:9], v[2:3], off offset:512
	global_load_dwordx2 v[20:21], v[2:3], off offset:1024
	global_load_dwordx2 v[26:27], v[0:1], off
	global_load_dwordx2 v[30:31], v[0:1], off offset:512
	global_load_dwordx2 v[34:35], v[0:1], off offset:1024
	global_load_dwordx2 v[38:39], v[0:1], off offset:1536
	s_mov_b32 s10, 0x280000
	global_load_dwordx2 v[2:3], v[2:3], off offset:1536
	v_mov_b32_e32 v19, v189
	s_waitcnt vmcnt(0)
	v_lshlrev_b32_e32 v6, 16, v4
	v_and_b32_e32 v7, 0xffff0000, v4
	v_lshlrev_b32_e32 v4, 16, v5
	v_and_b32_e32 v5, 0xffff0000, v5
	v_lshlrev_b32_e32 v28, 16, v26
	v_and_b32_e32 v29, 0xffff0000, v26
	v_lshlrev_b32_e32 v26, 16, v27
	v_and_b32_e32 v27, 0xffff0000, v27
	v_pk_add_f32 v[4:5], v[4:5], v[26:27]
	v_add_co_u32_e32 v26, vcc, s10, v0
	v_lshlrev_b32_e32 v10, 16, v8
	v_and_b32_e32 v11, 0xffff0000, v8
	v_lshlrev_b32_e32 v22, 16, v20
	v_and_b32_e32 v23, 0xffff0000, v20
	v_lshlrev_b32_e32 v32, 16, v30
	v_and_b32_e32 v33, 0xffff0000, v30
	v_lshlrev_b32_e32 v36, 16, v34
	v_and_b32_e32 v37, 0xffff0000, v34
	v_addc_co_u32_e32 v27, vcc, 0, v1, vcc
	v_pk_add_f32 v[6:7], v[6:7], v[28:29]
	v_pk_add_f32 v[10:11], v[10:11], v[32:33]
	v_pk_add_f32 v[22:23], v[22:23], v[36:37]
	global_load_dwordx2 v[28:29], v[26:27], off
	global_load_dwordx2 v[32:33], v[26:27], off offset:512
	global_load_dwordx2 v[36:37], v[26:27], off offset:1024
	v_lshlrev_b32_e32 v8, 16, v9
	global_load_dwordx2 v[26:27], v[26:27], off offset:1536
	v_and_b32_e32 v9, 0xffff0000, v9
	v_lshlrev_b32_e32 v24, 16, v2
	v_and_b32_e32 v25, 0xffff0000, v2
	v_lshlrev_b32_e32 v2, 16, v3
	v_and_b32_e32 v3, 0xffff0000, v3
	v_lshlrev_b32_e32 v30, 16, v31
	v_and_b32_e32 v31, 0xffff0000, v31
	v_lshlrev_b32_e32 v40, 16, v38
	v_and_b32_e32 v41, 0xffff0000, v38
	v_lshlrev_b32_e32 v38, 16, v39
	v_and_b32_e32 v39, 0xffff0000, v39
	v_pk_add_f32 v[8:9], v[8:9], v[30:31]
	v_pk_add_f32 v[2:3], v[2:3], v[38:39]
	v_pk_add_f32 v[24:25], v[24:25], v[40:41]
	s_mov_b32 s10, 0x500000
	v_lshlrev_b32_e32 v20, 16, v21
	v_and_b32_e32 v21, 0xffff0000, v21
	v_lshlrev_b32_e32 v34, 16, v35
	v_and_b32_e32 v35, 0xffff0000, v35
	v_pk_add_f32 v[20:21], v[20:21], v[34:35]
	s_waitcnt vmcnt(3)
	v_lshlrev_b32_e32 v30, 16, v28
	v_and_b32_e32 v31, 0xffff0000, v28
	v_lshlrev_b32_e32 v28, 16, v29
	v_and_b32_e32 v29, 0xffff0000, v29
	s_waitcnt vmcnt(0)
	v_lshlrev_b32_e32 v40, 16, v26
	v_and_b32_e32 v41, 0xffff0000, v26
	v_lshlrev_b32_e32 v26, 16, v27
	v_and_b32_e32 v27, 0xffff0000, v27
	v_pk_add_f32 v[28:29], v[4:5], v[28:29]
	v_pk_add_f32 v[4:5], v[6:7], v[30:31]
	v_pk_add_f32 v[30:31], v[24:25], v[40:41]
	v_pk_add_f32 v[24:25], v[2:3], v[26:27]
	v_add_co_u32_e32 v2, vcc, s10, v0
	v_lshlrev_b32_e32 v34, 16, v32
	v_and_b32_e32 v35, 0xffff0000, v32
	v_lshlrev_b32_e32 v32, 16, v33
	v_and_b32_e32 v33, 0xffff0000, v33
	v_lshlrev_b32_e32 v38, 16, v36
	v_and_b32_e32 v39, 0xffff0000, v36
	v_lshlrev_b32_e32 v36, 16, v37
	v_and_b32_e32 v37, 0xffff0000, v37
	v_addc_co_u32_e32 v3, vcc, 0, v1, vcc
	v_pk_add_f32 v[8:9], v[8:9], v[32:33]
	v_pk_add_f32 v[6:7], v[10:11], v[34:35]
	v_pk_add_f32 v[10:11], v[22:23], v[38:39]
	v_pk_add_f32 v[22:23], v[20:21], v[36:37]
	global_load_dwordx2 v[20:21], v[2:3], off
	global_load_dwordx2 v[32:33], v[2:3], off offset:512
	global_load_dwordx2 v[36:37], v[2:3], off offset:1024
	s_mov_b32 s10, 0x780000
	global_load_dwordx2 v[2:3], v[2:3], off offset:1536
	s_waitcnt vmcnt(3)
	v_lshlrev_b32_e32 v26, 16, v20
	v_and_b32_e32 v27, 0xffff0000, v20
	v_lshlrev_b32_e32 v20, 16, v21
	v_and_b32_e32 v21, 0xffff0000, v21
	s_waitcnt vmcnt(2)
	v_lshlrev_b32_e32 v34, 16, v32
	v_and_b32_e32 v35, 0xffff0000, v32
	v_lshlrev_b32_e32 v32, 16, v33
	v_and_b32_e32 v33, 0xffff0000, v33
	s_waitcnt vmcnt(1)
	v_lshlrev_b32_e32 v38, 16, v36
	v_and_b32_e32 v39, 0xffff0000, v36
	v_lshlrev_b32_e32 v36, 16, v37
	v_and_b32_e32 v37, 0xffff0000, v37
	s_waitcnt vmcnt(0)
	v_lshlrev_b32_e32 v40, 16, v2
	v_and_b32_e32 v41, 0xffff0000, v2
	v_lshlrev_b32_e32 v42, 16, v3
	v_and_b32_e32 v43, 0xffff0000, v3
	v_pk_add_f32 v[2:3], v[28:29], v[20:21]
	v_pk_add_f32 v[20:21], v[8:9], v[32:33]
	v_pk_add_f32 v[8:9], v[22:23], v[36:37]
	v_pk_add_f32 v[22:23], v[10:11], v[38:39]
	v_add_co_u32_e32 v10, vcc, s10, v0
	v_pk_add_f32 v[4:5], v[4:5], v[26:27]
	s_nop 0
	v_addc_co_u32_e32 v11, vcc, 0, v1, vcc
	global_load_dwordx2 v[28:29], v[10:11], off
	global_load_dwordx2 v[32:33], v[10:11], off offset:512
	global_load_dwordx2 v[36:37], v[10:11], off offset:1024
	v_pk_add_f32 v[6:7], v[6:7], v[34:35]
	global_load_dwordx2 v[10:11], v[10:11], off offset:1536
	v_pk_add_f32 v[26:27], v[30:31], v[40:41]
	s_mov_b32 s10, 0xa00000
	v_pk_add_f32 v[24:25], v[24:25], v[42:43]
	s_waitcnt vmcnt(3)
	v_lshlrev_b32_e32 v30, 16, v28
	v_and_b32_e32 v31, 0xffff0000, v28
	s_waitcnt vmcnt(2)
	v_lshlrev_b32_e32 v34, 16, v32
	v_and_b32_e32 v35, 0xffff0000, v32
	v_lshlrev_b32_e32 v32, 16, v33
	v_and_b32_e32 v33, 0xffff0000, v33
	s_waitcnt vmcnt(1)
	v_lshlrev_b32_e32 v38, 16, v36
	v_and_b32_e32 v39, 0xffff0000, v36
	v_lshlrev_b32_e32 v36, 16, v37
	v_and_b32_e32 v37, 0xffff0000, v37
	s_waitcnt vmcnt(0)
; __device__ __forceinline__ void load_bf16_row(const bf16* row, int lane, f32x4 (&v)[4]) {
;     const u32x2* p = (const u32x2*)row + lane;
; #pragma unroll
;     for (int j = 0; j < 4; ++j) { const u32x2 w = p[64 * j]; v[j] = (f32x4){bflo(w.x), bfhi(w.x), bflo(w.y), bfhi(w.y)}; }
; }
; template <int NSLICE> __device__ __forceinline__ void rms_phase(ArgP a, const float* g, bool final_out, int G) {
;     ...
; #pragma unroll
;         for (int sl = 0; sl < NSLICE; ++sl) {
;             f32x4 pv[4]; load_bf16_row(PART + (size_t)sl * (MP - R_META) * DM, lane, pv);
; #pragma unroll
;             for (int j = 0; j < 4; ++j) v[j] = v[j] + pv[j];
;         }
	v_lshlrev_b32_e32 v40, 16, v10
	v_and_b32_e32 v41, 0xffff0000, v10
	v_lshlrev_b32_e32 v42, 16, v11
	v_and_b32_e32 v43, 0xffff0000, v11
	v_pk_add_f32 v[10:11], v[4:5], v[30:31]
	v_pk_add_f32 v[4:5], v[20:21], v[32:33]
	v_pk_add_f32 v[20:21], v[6:7], v[34:35]
	v_pk_add_f32 v[6:7], v[22:23], v[38:39]
	v_pk_add_f32 v[22:23], v[8:9], v[36:37]
	v_pk_add_f32 v[8:9], v[26:27], v[40:41]
	v_add_co_u32_e32 v26, vcc, s10, v0
	v_lshlrev_b32_e32 v28, 16, v29
	v_and_b32_e32 v29, 0xffff0000, v29
	v_addc_co_u32_e32 v27, vcc, 0, v1, vcc
	v_pk_add_f32 v[2:3], v[2:3], v[28:29]
	global_load_dwordx2 v[28:29], v[26:27], off
	global_load_dwordx2 v[32:33], v[26:27], off offset:512
	global_load_dwordx2 v[36:37], v[26:27], off offset:1024
	v_pk_add_f32 v[24:25], v[24:25], v[42:43]
	global_load_dwordx2 v[26:27], v[26:27], off offset:1536
	s_mov_b32 s10, 0xc80000
	s_waitcnt vmcnt(3)
	v_lshlrev_b32_e32 v30, 16, v28
	v_and_b32_e32 v31, 0xffff0000, v28
	v_lshlrev_b32_e32 v28, 16, v29
	v_and_b32_e32 v29, 0xffff0000, v29
	s_waitcnt vmcnt(2)
	v_lshlrev_b32_e32 v34, 16, v32
	v_and_b32_e32 v35, 0xffff0000, v32
	v_lshlrev_b32_e32 v32, 16, v33
	v_and_b32_e32 v33, 0xffff0000, v33
	s_waitcnt vmcnt(1)
	v_lshlrev_b32_e32 v38, 16, v36
	v_and_b32_e32 v39, 0xffff0000, v36
	v_lshlrev_b32_e32 v36, 16, v37
	v_and_b32_e32 v37, 0xffff0000, v37
	s_waitcnt vmcnt(0)
	v_lshlrev_b32_e32 v40, 16, v26
	v_and_b32_e32 v41, 0xffff0000, v26
	v_lshlrev_b32_e32 v42, 16, v27
	v_and_b32_e32 v43, 0xffff0000, v27
	v_pk_add_f32 v[26:27], v[2:3], v[28:29]
	v_pk_add_f32 v[2:3], v[20:21], v[34:35]
	v_pk_add_f32 v[20:21], v[4:5], v[32:33]
	v_pk_add_f32 v[4:5], v[22:23], v[36:37]
	v_pk_add_f32 v[22:23], v[6:7], v[38:39]
	v_pk_add_f32 v[6:7], v[24:25], v[42:43]
	v_pk_add_f32 v[24:25], v[8:9], v[40:41]
	v_add_co_u32_e32 v8, vcc, s10, v0
	v_pk_add_f32 v[10:11], v[10:11], v[30:31]
	s_nop 0
	v_addc_co_u32_e32 v9, vcc, 0, v1, vcc
	global_load_dwordx2 v[28:29], v[8:9], off
	global_load_dwordx2 v[32:33], v[8:9], off offset:512
	global_load_dwordx2 v[36:37], v[8:9], off offset:1024
	s_mov_b32 s10, 0xf00000
	global_load_dwordx2 v[8:9], v[8:9], off offset:1536
	s_waitcnt vmcnt(3)
	v_lshlrev_b32_e32 v30, 16, v28
	v_and_b32_e32 v31, 0xffff0000, v28
	v_lshlrev_b32_e32 v28, 16, v29
	v_and_b32_e32 v29, 0xffff0000, v29
	s_waitcnt vmcnt(2)
	v_lshlrev_b32_e32 v34, 16, v32
	v_and_b32_e32 v35, 0xffff0000, v32
	v_lshlrev_b32_e32 v32, 16, v33
	v_and_b32_e32 v33, 0xffff0000, v33
	s_waitcnt vmcnt(1)
	v_lshlrev_b32_e32 v38, 16, v36
	v_and_b32_e32 v39, 0xffff0000, v36
	v_lshlrev_b32_e32 v36, 16, v37
	v_and_b32_e32 v37, 0xffff0000, v37
	s_waitcnt vmcnt(0)
	v_lshlrev_b32_e32 v40, 16, v8
	v_and_b32_e32 v41, 0xffff0000, v8
	v_lshlrev_b32_e32 v42, 16, v9
	v_and_b32_e32 v43, 0xffff0000, v9
	v_pk_add_f32 v[8:9], v[26:27], v[28:29]
	v_pk_add_f32 v[26:27], v[10:11], v[30:31]
	v_pk_add_f32 v[10:11], v[20:21], v[32:33]
	v_pk_add_f32 v[20:21], v[2:3], v[34:35]
	v_pk_add_f32 v[2:3], v[22:23], v[38:39]
	v_pk_add_f32 v[22:23], v[4:5], v[36:37]
	v_pk_add_f32 v[4:5], v[24:25], v[40:41]
	v_add_co_u32_e32 v24, vcc, s10, v0
	v_pk_add_f32 v[6:7], v[6:7], v[42:43]
	s_nop 0
	v_addc_co_u32_e32 v25, vcc, 0, v1, vcc
	global_load_dwordx2 v[28:29], v[24:25], off
	global_load_dwordx2 v[32:33], v[24:25], off offset:512
	global_load_dwordx2 v[36:37], v[24:25], off offset:1024
	s_mov_b32 s10, 0x1180000
	global_load_dwordx2 v[24:25], v[24:25], off offset:1536
	s_waitcnt vmcnt(3)
	v_lshlrev_b32_e32 v30, 16, v28
	v_and_b32_e32 v31, 0xffff0000, v28
	v_lshlrev_b32_e32 v28, 16, v29
	v_and_b32_e32 v29, 0xffff0000, v29
	s_waitcnt vmcnt(0)
	v_lshlrev_b32_e32 v40, 16, v24
	v_and_b32_e32 v41, 0xffff0000, v24
	v_lshlrev_b32_e32 v24, 16, v25
	v_and_b32_e32 v25, 0xffff0000, v25
	v_pk_add_f32 v[6:7], v[6:7], v[24:25]
	v_add_co_u32_e32 v24, vcc, s10, v0
	v_lshlrev_b32_e32 v34, 16, v32
	v_and_b32_e32 v35, 0xffff0000, v32
	v_lshlrev_b32_e32 v32, 16, v33
	v_and_b32_e32 v33, 0xffff0000, v33
	v_lshlrev_b32_e32 v38, 16, v36
	v_and_b32_e32 v39, 0xffff0000, v36
	v_lshlrev_b32_e32 v36, 16, v37
	v_and_b32_e32 v37, 0xffff0000, v37
	v_addc_co_u32_e32 v25, vcc, 0, v1, vcc
	v_pk_add_f32 v[8:9], v[8:9], v[28:29]
	v_pk_add_f32 v[10:11], v[10:11], v[32:33]
	v_pk_add_f32 v[22:23], v[22:23], v[36:37]
	global_load_dwordx2 v[28:29], v[24:25], off
	global_load_dwordx2 v[32:33], v[24:25], off offset:512
	global_load_dwordx2 v[36:37], v[24:25], off offset:1024
	v_pk_add_f32 v[4:5], v[4:5], v[40:41]
	global_load_dwordx2 v[24:25], v[24:25], off offset:1536
	s_mov_b32 s10, 0x1400000
	v_pk_add_f32 v[26:27], v[26:27], v[30:31]
	v_pk_add_f32 v[20:21], v[20:21], v[34:35]
	v_pk_add_f32 v[2:3], v[2:3], v[38:39]
	s_waitcnt vmcnt(3)
	v_lshlrev_b32_e32 v30, 16, v28
	v_and_b32_e32 v31, 0xffff0000, v28
	v_lshlrev_b32_e32 v28, 16, v29
	v_and_b32_e32 v29, 0xffff0000, v29
	s_waitcnt vmcnt(0)
	v_lshlrev_b32_e32 v40, 16, v24
	v_and_b32_e32 v41, 0xffff0000, v24
	v_lshlrev_b32_e32 v24, 16, v25
	v_and_b32_e32 v25, 0xffff0000, v25
	v_pk_add_f32 v[6:7], v[6:7], v[24:25]
	v_add_co_u32_e32 v24, vcc, s10, v0
	v_lshlrev_b32_e32 v34, 16, v32
	v_and_b32_e32 v35, 0xffff0000, v32
	v_lshlrev_b32_e32 v32, 16, v33
	v_and_b32_e32 v33, 0xffff0000, v33
	v_lshlrev_b32_e32 v38, 16, v36
	v_and_b32_e32 v39, 0xffff0000, v36
	v_lshlrev_b32_e32 v36, 16, v37
	v_and_b32_e32 v37, 0xffff0000, v37
	v_addc_co_u32_e32 v25, vcc, 0, v1, vcc
	v_pk_add_f32 v[8:9], v[8:9], v[28:29]
	v_pk_add_f32 v[10:11], v[10:11], v[32:33]
	v_pk_add_f32 v[22:23], v[22:23], v[36:37]
	global_load_dwordx2 v[28:29], v[24:25], off
	global_load_dwordx2 v[32:33], v[24:25], off offset:512
	global_load_dwordx2 v[36:37], v[24:25], off offset:1024
	v_pk_add_f32 v[20:21], v[20:21], v[34:35]
	global_load_dwordx2 v[24:25], v[24:25], off offset:1536
	v_pk_add_f32 v[4:5], v[4:5], v[40:41]
	s_mov_b32 s10, 0x1680000
	v_pk_add_f32 v[26:27], v[26:27], v[30:31]
	v_pk_add_f32 v[2:3], v[2:3], v[38:39]
	s_waitcnt vmcnt(3)
; template <int NSLICE> __device__ __forceinline__ void rms_phase(ArgP a, const float* g, bool final_out, int G) {
;     ...
; #pragma unroll
;         for (int sl = 0; sl < NSLICE; ++sl) {
;             f32x4 pv[4]; load_bf16_row(PART + (size_t)sl * (MP - R_META) * DM, lane, pv);
; #pragma unroll
;             for (int j = 0; j < 4; ++j) v[j] = v[j] + pv[j];
;         }
;         if (!final_out) store_bf16_row(H + (size_t)m * DM, lane, v);
;         float rs; f32x4 y[4]; rms_row(v, g, lane, rs, y);
	v_lshlrev_b32_e32 v30, 16, v28
	s_waitcnt vmcnt(2)
	v_lshlrev_b32_e32 v34, 16, v32
	v_and_b32_e32 v35, 0xffff0000, v32
	v_lshlrev_b32_e32 v32, 16, v33
	v_and_b32_e32 v33, 0xffff0000, v33
	s_waitcnt vmcnt(0)
	v_lshlrev_b32_e32 v40, 16, v24
	v_and_b32_e32 v41, 0xffff0000, v24
	v_pk_add_f32 v[10:11], v[10:11], v[32:33]
	v_pk_add_f32 v[32:33], v[4:5], v[40:41]
	v_add_co_u32_e32 v4, vcc, s10, v0
	v_and_b32_e32 v31, 0xffff0000, v28
	v_lshlrev_b32_e32 v28, 16, v29
	v_and_b32_e32 v29, 0xffff0000, v29
	v_lshlrev_b32_e32 v24, 16, v25
	v_and_b32_e32 v25, 0xffff0000, v25
	v_addc_co_u32_e32 v5, vcc, 0, v1, vcc
	v_pk_add_f32 v[8:9], v[8:9], v[28:29]
	v_pk_add_f32 v[28:29], v[20:21], v[34:35]
	v_pk_add_f32 v[6:7], v[6:7], v[24:25]
	global_load_dwordx2 v[20:21], v[4:5], off
	global_load_dwordx2 v[24:25], v[4:5], off offset:512
	v_lshlrev_b32_e32 v38, 16, v36
	v_and_b32_e32 v39, 0xffff0000, v36
	v_lshlrev_b32_e32 v36, 16, v37
	v_and_b32_e32 v37, 0xffff0000, v37
	v_pk_add_f32 v[26:27], v[26:27], v[30:31]
	v_pk_add_f32 v[30:31], v[22:23], v[36:37]
	s_mov_b32 s10, 0x1900000
	v_pk_add_f32 v[2:3], v[2:3], v[38:39]
	s_waitcnt vmcnt(1)
	v_lshlrev_b32_e32 v22, 16, v20
	s_waitcnt vmcnt(0)
	v_lshlrev_b32_e32 v34, 16, v24
	v_and_b32_e32 v35, 0xffff0000, v24
	v_lshlrev_b32_e32 v36, 16, v25
	v_and_b32_e32 v37, 0xffff0000, v25
	global_load_dwordx2 v[24:25], v[4:5], off offset:1024
	v_and_b32_e32 v23, 0xffff0000, v20
	v_lshlrev_b32_e32 v20, 16, v21
	v_and_b32_e32 v21, 0xffff0000, v21
	v_pk_add_f32 v[20:21], v[8:9], v[20:21]
	v_pk_add_f32 v[8:9], v[10:11], v[36:37]
	v_add_co_u32_e32 v36, vcc, s10, v0
	s_load_dwordx2 s[10:11], s[0:1], 0x78
	s_nop 0
	v_addc_co_u32_e32 v37, vcc, 0, v1, vcc
	global_load_dwordx2 v[0:1], v[36:37], off
	s_waitcnt vmcnt(1)
	v_lshlrev_b32_e32 v38, 16, v24
	global_load_dwordx2 v[4:5], v[4:5], off offset:1536
	v_and_b32_e32 v39, 0xffff0000, v24
	v_lshlrev_b32_e32 v40, 16, v25
	v_and_b32_e32 v41, 0xffff0000, v25
	v_pk_add_f32 v[24:25], v[26:27], v[22:23]
	v_pk_add_f32 v[22:23], v[28:29], v[34:35]
	global_load_dwordx2 v[28:29], v[36:37], off offset:512
	global_load_dwordx2 v[34:35], v[36:37], off offset:1024
	v_pk_add_f32 v[10:11], v[30:31], v[40:41]
	global_load_dwordx2 v[36:37], v[36:37], off offset:1536
	s_waitcnt vmcnt(4)
	v_lshlrev_b32_e32 v26, 16, v0
	v_and_b32_e32 v27, 0xffff0000, v0
	v_lshlrev_b32_e32 v0, 16, v1
	v_and_b32_e32 v1, 0xffff0000, v1
	v_pk_add_f32 v[0:1], v[20:21], v[0:1]
	s_waitcnt vmcnt(3)
	v_lshlrev_b32_e32 v42, 16, v4
	v_and_b32_e32 v43, 0xffff0000, v4
	v_lshlrev_b32_e32 v44, 16, v5
	v_and_b32_e32 v45, 0xffff0000, v5
	v_pk_add_f32 v[4:5], v[2:3], v[38:39]
	v_pk_add_f32 v[2:3], v[32:33], v[42:43]
	s_waitcnt vmcnt(2)
	v_lshlrev_b32_e32 v30, 16, v28
	v_and_b32_e32 v31, 0xffff0000, v28
	v_lshlrev_b32_e32 v28, 16, v29
	v_and_b32_e32 v29, 0xffff0000, v29
	s_waitcnt vmcnt(1)
	v_lshlrev_b32_e32 v32, 16, v34
	v_and_b32_e32 v33, 0xffff0000, v34
	v_lshlrev_b32_e32 v34, 16, v35
	v_and_b32_e32 v35, 0xffff0000, v35
	s_waitcnt vmcnt(0)
; __device__ __forceinline__ void rms_row(const f32x4 (&v)[4], const float* g, int lane, float& rs, f32x4 (&y)[4]) {
;     float s = 0.f;
; #pragma unroll
;     for (int j = 0; j < 4; ++j) s += (v[j].x * v[j].x + v[j].y * v[j].y) + (v[j].z * v[j].z + v[j].w * v[j].w);
;     rs = __builtin_amdgcn_rsqf(wave_sum(s) * (1.f / DM) + EPS);
; #pragma unroll
;     for (int j = 0; j < 4; ++j) { const f32x4 gv = *((const f32x4*)g + lane + 64 * j); y[j] = v[j] * rs * gv; }
; }
; template <int NSLICE> __device__ __forceinline__ void rms_phase(ArgP a, const float* g, bool final_out, int G) {
;     ...
;         float rs; f32x4 y[4]; rms_row(v, g, lane, rs, y);
;         if (!final_out) store_bf16_row(XN + (size_t)m * DM, lane, y);
;         else { float* o = a->out + O_YS + (size_t)(m - R_SAMP) * DM;
; #pragma unroll
;             for (int j = 0; j < 4; ++j) *((f32x4*)o + lane + 64 * j) = y[j]; }
	v_lshlrev_b32_e32 v38, 16, v36
	v_and_b32_e32 v39, 0xffff0000, v36
	v_lshlrev_b32_e32 v40, 16, v37
	v_and_b32_e32 v41, 0xffff0000, v37
	v_pk_add_f32 v[36:37], v[24:25], v[26:27]
	v_pk_add_f32 v[6:7], v[6:7], v[44:45]
	v_pk_add_f32 v[26:27], v[22:23], v[30:31]
	v_pk_add_f32 v[28:29], v[8:9], v[28:29]
	v_pk_add_f32 v[8:9], v[10:11], v[34:35]
	v_pk_add_f32 v[10:11], v[4:5], v[32:33]
	v_pk_add_f32 v[22:23], v[2:3], v[38:39]
	v_pk_mul_f32 v[2:3], v[0:1], v[0:1]
	v_pk_mul_f32 v[4:5], v[36:37], v[36:37]
	v_pk_add_f32 v[20:21], v[6:7], v[40:41]
	v_pk_mov_b32 v[6:7], v[4:5], v[2:3] op_sel:[1,0]
	v_mov_b32_e32 v5, v3
	v_pk_add_f32 v[2:3], v[6:7], v[4:5]
	v_pk_mul_f32 v[4:5], v[28:29], v[28:29]
	v_pk_add_f32 v[2:3], v[2:3], v[2:3] op_sel_hi:[0,1]
	v_pk_mul_f32 v[6:7], v[26:27], v[26:27]
	v_mul_f32_e32 v2, v10, v10
	v_pk_mov_b32 v[24:25], v[6:7], v[4:5] op_sel:[1,0]
	v_mov_b32_e32 v7, v5
	v_pk_add_f32 v[4:5], v[24:25], v[6:7]
	v_pk_fma_f32 v[6:7], v[10:11], v[10:11], v[2:3] op_sel_hi:[1,1,0]
	v_mul_f32_e32 v2, v8, v8
	v_pk_add_f32 v[4:5], v[4:5], v[4:5] op_sel_hi:[0,1]
	v_pk_fma_f32 v[24:25], v[8:9], v[8:9], v[2:3] op_sel_hi:[1,1,0]
	v_mul_f32_e32 v6, v22, v22
	v_mul_f32_e32 v24, v23, v23
	v_mul_f32_e32 v2, v20, v20
	v_mul_f32_e32 v4, v21, v21
	v_pk_add_f32 v[6:7], v[6:7], v[24:25]
	v_pk_add_f32 v[2:3], v[2:3], v[4:5]
	v_xor_b32_e32 v4, 1, v208
	v_pk_add_f32 v[2:3], v[6:7], v[2:3]
	s_nop 0
	v_add_f32_e32 v2, v2, v3
	v_and_b32_e32 v3, 64, v208
	v_add_u32_e32 v3, 64, v3
	v_cmp_lt_i32_e32 vcc, v4, v3
	s_nop 1
	v_cndmask_b32_e32 v4, v208, v4, vcc
	v_lshlrev_b32_e32 v4, 2, v4
	ds_bpermute_b32 v4, v4, v2
	s_waitcnt lgkmcnt(0)
	v_add_f32_e32 v2, v2, v4
	v_xor_b32_e32 v4, 2, v208
	v_cmp_lt_i32_e32 vcc, v4, v3
	s_nop 1
	v_cndmask_b32_e32 v4, v208, v4, vcc
	v_lshlrev_b32_e32 v4, 2, v4
	ds_bpermute_b32 v4, v4, v2
	s_waitcnt lgkmcnt(0)
	v_add_f32_e32 v2, v2, v4
	v_xor_b32_e32 v4, 4, v208
	v_cmp_lt_i32_e32 vcc, v4, v3
	s_nop 1
	v_cndmask_b32_e32 v4, v208, v4, vcc
	v_lshlrev_b32_e32 v4, 2, v4
	ds_bpermute_b32 v4, v4, v2
	s_waitcnt lgkmcnt(0)
	v_add_f32_e32 v2, v2, v4
	v_xor_b32_e32 v4, 8, v208
	v_cmp_lt_i32_e32 vcc, v4, v3
	s_nop 1
	v_cndmask_b32_e32 v4, v208, v4, vcc
	v_lshlrev_b32_e32 v4, 2, v4
	ds_bpermute_b32 v4, v4, v2
	s_waitcnt lgkmcnt(0)
	v_add_f32_e32 v2, v2, v4
	v_xor_b32_e32 v4, 16, v208
	v_cmp_lt_i32_e32 vcc, v4, v3
	s_nop 1
	v_cndmask_b32_e32 v4, v208, v4, vcc
	v_lshlrev_b32_e32 v4, 2, v4
	ds_bpermute_b32 v4, v4, v2
	s_waitcnt lgkmcnt(0)
	v_add_f32_e32 v2, v2, v4
	v_xor_b32_e32 v4, 32, v208
	v_cmp_lt_i32_e32 vcc, v4, v3
	s_nop 1
	v_cndmask_b32_e32 v3, v208, v4, vcc
	global_load_dwordx4 v[4:7], v[16:17], off
	v_lshlrev_b32_e32 v3, 2, v3
	ds_bpermute_b32 v3, v3, v2
	s_waitcnt lgkmcnt(0)
	v_add_f32_e32 v2, v2, v3
	v_fmamk_f32 v2, v2, 0x3a800000, v207
	v_rsq_f32_e32 v24, v2
	s_nop 0
	v_pk_mul_f32 v[30:31], v[36:37], v[24:25] op_sel_hi:[1,0]
	v_pk_mul_f32 v[0:1], v[0:1], v[24:25] op_sel_hi:[1,0]
	v_pk_mul_f32 v[26:27], v[26:27], v[24:25] op_sel_hi:[1,0]
	v_pk_mul_f32 v[28:29], v[28:29], v[24:25] op_sel_hi:[1,0]
	v_pk_mul_f32 v[8:9], v[8:9], v[24:25] op_sel_hi:[1,0]
	v_pk_mul_f32 v[20:21], v[20:21], v[24:25] op_sel_hi:[1,0]
	s_waitcnt vmcnt(0)
	v_pk_mul_f32 v[2:3], v[6:7], v[0:1]
	v_pk_mul_f32 v[0:1], v[4:5], v[30:31]
	global_load_dwordx4 v[4:7], v[16:17], off offset:1024
	v_pk_mul_f32 v[30:31], v[10:11], v[24:25] op_sel_hi:[1,0]
	s_waitcnt vmcnt(0)
	v_pk_mul_f32 v[6:7], v[6:7], v[28:29]
	v_pk_mul_f32 v[4:5], v[4:5], v[26:27]
	global_load_dwordx4 v[26:29], v[16:17], off offset:2048
	s_waitcnt vmcnt(0)
	v_pk_mul_f32 v[10:11], v[28:29], v[8:9]
	v_pk_mul_f32 v[8:9], v[26:27], v[30:31]
	global_load_dwordx4 v[26:29], v[16:17], off offset:3072
	v_pk_mul_f32 v[30:31], v[22:23], v[24:25] op_sel_hi:[1,0]
	v_add_u32_e32 v24, 0xffffbf80, v188
	v_mov_b32_e32 v25, v189
	v_lshlrev_b64 v[24:25], 12, v[24:25]
	v_lshl_add_u64 v[24:25], s[10:11], 0, v[24:25]
	v_lshl_add_u64 v[24:25], v[24:25], 0, v[18:19]
	s_mov_b64 s[10:11], 0x4000000
	s_waitcnt vmcnt(0)
	v_pk_mul_f32 v[22:23], v[28:29], v[20:21]
	v_pk_mul_f32 v[20:21], v[26:27], v[30:31]
	v_lshl_add_u64 v[26:27], v[24:25], 0, s[10:11]
	v_add_co_u32_e32 v24, vcc, 0x4000000, v24
	s_nop 1
	v_addc_co_u32_e32 v25, vcc, 0, v25, vcc
	global_store_dwordx4 v[24:25], v[0:3], off sc1
	global_store_dwordx4 v[26:27], v[4:7], off offset:1024 sc1
	global_store_dwordx4 v[26:27], v[8:11], off offset:2048 sc1
	global_store_dwordx4 v[26:27], v[20:23], off offset:3072 sc1
	s_branch .LBB0_1327
